# baseline (speedup 1.0000x reference)
; __device__ __forceinline__ float bf_lo(u32 v) { return __uint_as_float(v << 16); }
; __device__ __forceinline__ float bf_hi(u32 v) { return __uint_as_float(v & 0xffff0000u); }
; template <bool FOX>
; __device__ __forceinline__ void attn_pair(const Params& p, int it, char* smem, const int wv) {
;     ...
;     {
;       const int tid3 = opaque_tid(wv);
;       const int e_lane = tid3 & 63, e_fr = e_lane & 15, e_fq = e_lane >> 4, e_qw = q0 + wv * 32;
;       #pragma unroll
;       for (int qt = 0; qt < 2; ++qt) {
;         const float inv = FOX ? 1.0f / st1[qt] : 1.0f;
;         u16* yrow = Yp + (tok0 + e_qw + qt * 16 + e_fr) * ld + e_fq * 4;
;         #pragma unroll
;         for (int dt = 0; dt < 8; ++dt) {
;           uint2 g = *(const uint2*)(yrow + dt * 16);
;           uint2 pk;
;           pk.x = pack2(o[dt][qt][0] * inv * bf_lo(g.x), o[dt][qt][1] * inv * bf_hi(g.x));
;           pk.y = pack2(o[dt][qt][2] * inv * bf_lo(g.y), o[dt][qt][3] * inv * bf_hi(g.y));
;           *(uint2*)(yrow + dt * 16) = pk;
;         }
;       }
;     }
.LBB0_714:
	v_mbcnt_lo_u32_b32 v228, -1, 0
	v_mbcnt_hi_u32_b32 v228, -1, v228
	v_and_b32_e32 v228, 16, v228
	v_lshrrev_b32_e32 v229, 1, v228
	v_add_u32_e32 v228, v228, v229
	v_mov_b32_e32 v229, 0
	s_lshl_b32 s0, s40, 1
	s_barrier
	v_mbcnt_lo_u32_b32 v0, -1, 0
	v_mbcnt_hi_u32_b32 v0, -1, v0
	s_add_u32 s0, s3, s0
	v_and_or_b32 v36, v0, 15, s43
	v_lshrrev_b32_e32 v0, 1, v0
	s_addc_u32 s1, s36, 0
	v_and_b32_e32 v0, 24, v0
	v_lshl_add_u64 v[34:35], s[0:1], 0, v[0:1]
	v_mad_u64_u32 v[34:35], s[0:1], v36, s25, v[34:35]
	v_mad_i32_i24 v35, s39, v120, v35
	v_lshl_add_u64 v[252:253], v[34:35], 0, v[228:229]
	global_load_dwordx4 v[232:235], v[252:253], off
	global_load_dwordx4 v[236:239], v[252:253], off offset:64
	global_load_dwordx4 v[240:243], v[252:253], off offset:128
	global_load_dwordx4 v[244:247], v[252:253], off offset:192
	v_div_scale_f32 v0, s[0:1], v137, v137, 1.0
	v_rcp_f32_e32 v62, v0
	v_div_scale_f32 v63, vcc, 1.0, v137, 1.0
	v_fma_f32 v36, -v0, v62, 1.0
	v_fmac_f32_e32 v62, v36, v62
	v_mul_f32_e32 v64, v63, v62
	v_add_co_u32_e64 v36, s[0:1], s26, v34
	v_fma_f32 v65, -v0, v64, v63
	s_nop 0
	v_addc_co_u32_e64 v37, s[0:1], 0, v35, s[0:1]
	v_fmac_f32_e32 v64, v65, v62
	v_lshl_add_u64 v[222:223], v[36:37], 0, v[228:229]
	global_load_dwordx4 v[248:251], v[222:223], off
	v_fma_f32 v0, -v0, v64, v63
	v_div_fmas_f32 v0, v0, v62, v64
	v_div_fixup_f32 v0, v0, v137, 1.0
	v_pk_mul_f32 v[62:63], v[94:95], v[0:1] op_sel_hi:[1,0]
	v_pk_mul_f32 v[64:65], v[96:97], v[0:1] op_sel_hi:[1,0]
	v_pk_mul_f32 v[66:67], v[90:91], v[0:1] op_sel_hi:[1,0]
	v_pk_mul_f32 v[68:69], v[92:93], v[0:1] op_sel_hi:[1,0]
	v_pk_mul_f32 v[86:87], v[86:87], v[0:1] op_sel_hi:[1,0]
	v_pk_mul_f32 v[88:89], v[88:89], v[0:1] op_sel_hi:[1,0]
	v_pk_mul_f32 v[82:83], v[82:83], v[0:1] op_sel_hi:[1,0]
	v_pk_mul_f32 v[84:85], v[84:85], v[0:1] op_sel_hi:[1,0]
	v_pk_mul_f32 v[78:79], v[78:79], v[0:1] op_sel_hi:[1,0]
	v_pk_mul_f32 v[46:47], v[46:47], v[0:1] op_sel_hi:[1,0]
	v_pk_mul_f32 v[48:49], v[48:49], v[0:1] op_sel_hi:[1,0]
	s_waitcnt vmcnt(4)
	v_permlane16_swap_b32_e32 v232, v234
	v_permlane16_swap_b32_e32 v233, v235
	v_mov_b32_e32 v38, v232
	v_mov_b32_e32 v39, v233
	v_lshlrev_b32_e32 v90, 16, v38
	v_and_b32_e32 v91, 0xffff0000, v38
	v_lshlrev_b32_e32 v38, 16, v39
	v_and_b32_e32 v39, 0xffff0000, v39
	s_waitcnt vmcnt(4)
	v_mov_b32_e32 v40, v234
	v_mov_b32_e32 v41, v235
	v_lshlrev_b32_e32 v92, 16, v40
	v_and_b32_e32 v93, 0xffff0000, v40
	v_lshlrev_b32_e32 v40, 16, v41
	v_and_b32_e32 v41, 0xffff0000, v41
	s_waitcnt vmcnt(3)
	v_permlane16_swap_b32_e32 v236, v238
	v_permlane16_swap_b32_e32 v237, v239
	v_mov_b32_e32 v42, v236
	v_mov_b32_e32 v43, v237
	v_lshlrev_b32_e32 v94, 16, v42
	v_and_b32_e32 v95, 0xffff0000, v42
	v_lshlrev_b32_e32 v42, 16, v43
	v_and_b32_e32 v43, 0xffff0000, v43
	s_waitcnt vmcnt(3)
	v_mov_b32_e32 v44, v238
	v_mov_b32_e32 v45, v239
	v_lshlrev_b32_e32 v96, 16, v44
	v_and_b32_e32 v97, 0xffff0000, v44
	v_lshlrev_b32_e32 v44, 16, v45
	v_and_b32_e32 v45, 0xffff0000, v45
	v_pk_mul_f32 v[62:63], v[62:63], v[90:91]
	v_pk_mul_f32 v[38:39], v[64:65], v[38:39]
	v_pk_mul_f32 v[64:65], v[66:67], v[92:93]
	v_pk_mul_f32 v[40:41], v[68:69], v[40:41]
	v_pk_mul_f32 v[66:67], v[86:87], v[94:95]
	v_pk_mul_f32 v[42:43], v[88:89], v[42:43]
	v_pk_mul_f32 v[68:69], v[82:83], v[96:97]
	v_pk_mul_f32 v[44:45], v[84:85], v[44:45]
	v_cvt_pk_bf16_f32 v62, v62, v63
	v_cvt_pk_bf16_f32 v63, v38, v39
	v_cvt_pk_bf16_f32 v38, v64, v65
	v_cvt_pk_bf16_f32 v39, v40, v41
	v_cvt_pk_bf16_f32 v40, v66, v67
	v_cvt_pk_bf16_f32 v41, v42, v43
	v_cvt_pk_bf16_f32 v42, v68, v69
	v_cvt_pk_bf16_f32 v43, v44, v45
	v_mov_b32_e32 v224, v62
	v_mov_b32_e32 v225, v63
	v_mov_b32_e32 v226, v38
	v_mov_b32_e32 v227, v39
	v_lshl_add_u64 v[230:231], v[34:35], 0, v[228:229]
	s_nop 0
	v_permlane16_swap_b32_e32 v224, v226
	v_permlane16_swap_b32_e32 v225, v227
	global_store_dwordx4 v[230:231], v[224:227], off
	s_nop 1
	v_mov_b32_e32 v224, v40
	v_mov_b32_e32 v225, v41
	v_mov_b32_e32 v226, v42
	v_mov_b32_e32 v227, v43
	v_lshl_add_u64 v[230:231], v[34:35], 0, v[228:229]
	s_nop 0
	v_permlane16_swap_b32_e32 v224, v226
	v_permlane16_swap_b32_e32 v225, v227
	global_store_dwordx4 v[230:231], v[224:227], off offset:64
	s_nop 1
	s_waitcnt vmcnt(4)
	v_permlane16_swap_b32_e32 v240, v242
	v_permlane16_swap_b32_e32 v241, v243
	v_mov_b32_e32 v50, v240
	v_mov_b32_e32 v51, v241
	v_lshlrev_b32_e32 v98, 16, v50
	v_and_b32_e32 v99, 0xffff0000, v50
	v_lshlrev_b32_e32 v40, 16, v51
	global_load_dwordx4 v[232:235], v[222:223], off offset:64
	v_and_b32_e32 v41, 0xffff0000, v51
	v_pk_mul_f32 v[44:45], v[80:81], v[0:1] op_sel_hi:[1,0]
	v_pk_mul_f32 v[78:79], v[78:79], v[98:99]
	v_pk_mul_f32 v[40:41], v[44:45], v[40:41]
	v_cvt_pk_bf16_f32 v38, v78, v79
	v_cvt_pk_bf16_f32 v39, v40, v41
	v_mov_b32_e32 v224, v38
	v_mov_b32_e32 v225, v39
	s_waitcnt vmcnt(5)
	v_mov_b32_e32 v52, v242
	v_mov_b32_e32 v53, v243
	v_lshlrev_b32_e32 v38, 16, v52
	v_and_b32_e32 v39, 0xffff0000, v52
	v_pk_mul_f32 v[40:41], v[74:75], v[0:1] op_sel_hi:[1,0]
	v_lshlrev_b32_e32 v44, 16, v53
	v_and_b32_e32 v45, 0xffff0000, v53
	v_pk_mul_f32 v[50:51], v[76:77], v[0:1] op_sel_hi:[1,0]
	v_pk_mul_f32 v[38:39], v[40:41], v[38:39]
	v_pk_mul_f32 v[44:45], v[50:51], v[44:45]
	v_cvt_pk_bf16_f32 v38, v38, v39
	v_cvt_pk_bf16_f32 v39, v44, v45
	v_mov_b32_e32 v226, v38
	v_mov_b32_e32 v227, v39
	v_lshl_add_u64 v[230:231], v[34:35], 0, v[228:229]
	s_nop 0
	v_permlane16_swap_b32_e32 v224, v226
	v_permlane16_swap_b32_e32 v225, v227
	global_store_dwordx4 v[230:231], v[224:227], off offset:128
	s_nop 1
	s_waitcnt vmcnt(5)
; __device__ __forceinline__ float bf_lo(u32 v) { return __uint_as_float(v << 16); }
; __device__ __forceinline__ float bf_hi(u32 v) { return __uint_as_float(v & 0xffff0000u); }
; template <bool FOX>
; __device__ __forceinline__ void attn_pair(const Params& p, int it, char* smem, const int wv) {
;     ...
;       #pragma unroll
;       for (int qt = 0; qt < 2; ++qt) {
;         const float inv = FOX ? 1.0f / st1[qt] : 1.0f;
;         u16* yrow = Yp + (tok0 + e_qw + qt * 16 + e_fr) * ld + e_fq * 4;
;         #pragma unroll
;         for (int dt = 0; dt < 8; ++dt) {
;           uint2 g = *(const uint2*)(yrow + dt * 16);
;           uint2 pk;
;           pk.x = pack2(o[dt][qt][0] * inv * bf_lo(g.x), o[dt][qt][1] * inv * bf_hi(g.x));
;           pk.y = pack2(o[dt][qt][2] * inv * bf_lo(g.y), o[dt][qt][3] * inv * bf_hi(g.y));
;           *(uint2*)(yrow + dt * 16) = pk;
;         }
;       }
	v_permlane16_swap_b32_e32 v244, v246
	v_permlane16_swap_b32_e32 v245, v247
	v_mov_b32_e32 v54, v244
	v_mov_b32_e32 v55, v245
	v_lshlrev_b32_e32 v38, 16, v54
	v_and_b32_e32 v39, 0xffff0000, v54
	v_pk_mul_f32 v[44:45], v[70:71], v[0:1] op_sel_hi:[1,0]
	v_lshlrev_b32_e32 v50, 16, v55
	v_and_b32_e32 v51, 0xffff0000, v55
	v_pk_mul_f32 v[52:53], v[72:73], v[0:1] op_sel_hi:[1,0]
	v_pk_mul_f32 v[38:39], v[44:45], v[38:39]
	v_pk_mul_f32 v[50:51], v[52:53], v[50:51]
	global_load_dwordx4 v[236:239], v[222:223], off offset:128
	v_cvt_pk_bf16_f32 v38, v38, v39
	v_cvt_pk_bf16_f32 v39, v50, v51
	v_mov_b32_e32 v224, v38
	v_mov_b32_e32 v225, v39
	s_waitcnt vmcnt(6)
	v_mov_b32_e32 v56, v246
	v_mov_b32_e32 v57, v247
	v_lshlrev_b32_e32 v38, 16, v56
	v_and_b32_e32 v39, 0xffff0000, v56
	v_pk_mul_f32 v[38:39], v[46:47], v[38:39]
	v_lshlrev_b32_e32 v46, 16, v57
	v_and_b32_e32 v47, 0xffff0000, v57
	v_div_scale_f32 v0, s[0:1], v130, v130, 1.0
	v_pk_mul_f32 v[46:47], v[48:49], v[46:47]
	v_rcp_f32_e32 v48, v0
	v_cvt_pk_bf16_f32 v38, v38, v39
	v_cvt_pk_bf16_f32 v39, v46, v47
	v_mov_b32_e32 v226, v38
	v_mov_b32_e32 v227, v39
	v_lshl_add_u64 v[230:231], v[34:35], 0, v[228:229]
	s_nop 0
	v_permlane16_swap_b32_e32 v224, v226
	v_permlane16_swap_b32_e32 v225, v227
	global_store_dwordx4 v[230:231], v[224:227], off offset:192
	s_nop 1
	v_fma_f32 v34, -v0, v48, 1.0
	global_load_dwordx4 v[240:243], v[222:223], off offset:192
	v_fmac_f32_e32 v48, v34, v48
	v_div_scale_f32 v34, vcc, 1.0, v130, 1.0
	v_mul_f32_e32 v38, v34, v48
	v_fma_f32 v35, -v0, v38, v34
	v_fmac_f32_e32 v38, v35, v48
	v_fma_f32 v0, -v0, v38, v34
	v_div_fmas_f32 v0, v0, v48, v38
	v_div_fixup_f32 v0, v0, v130, 1.0
	s_waitcnt vmcnt(7)
	v_permlane16_swap_b32_e32 v248, v250
	v_permlane16_swap_b32_e32 v249, v251
	v_mov_b32_e32 v58, v248
	v_mov_b32_e32 v59, v249
	v_lshlrev_b32_e32 v38, 16, v58
	v_and_b32_e32 v39, 0xffff0000, v58
	v_pk_mul_f32 v[30:31], v[30:31], v[0:1] op_sel_hi:[1,0]
	v_pk_mul_f32 v[32:33], v[32:33], v[0:1] op_sel_hi:[1,0]
	v_pk_mul_f32 v[30:31], v[30:31], v[38:39]
	v_lshlrev_b32_e32 v38, 16, v59
	v_and_b32_e32 v39, 0xffff0000, v59
	v_pk_mul_f32 v[32:33], v[32:33], v[38:39]
	v_cvt_pk_bf16_f32 v30, v30, v31
	v_cvt_pk_bf16_f32 v31, v32, v33
	v_mov_b32_e32 v224, v30
	v_mov_b32_e32 v225, v31
	s_waitcnt vmcnt(7)
	v_mov_b32_e32 v60, v250
	v_mov_b32_e32 v61, v251
	v_lshlrev_b32_e32 v30, 16, v60
	v_and_b32_e32 v31, 0xffff0000, v60
	v_pk_mul_f32 v[26:27], v[26:27], v[0:1] op_sel_hi:[1,0]
	v_pk_mul_f32 v[28:29], v[28:29], v[0:1] op_sel_hi:[1,0]
	v_pk_mul_f32 v[26:27], v[26:27], v[30:31]
	v_lshlrev_b32_e32 v30, 16, v61
	v_and_b32_e32 v31, 0xffff0000, v61
	v_pk_mul_f32 v[28:29], v[28:29], v[30:31]
	v_cvt_pk_bf16_f32 v26, v26, v27
	v_cvt_pk_bf16_f32 v27, v28, v29
	v_mov_b32_e32 v226, v26
	v_mov_b32_e32 v227, v27
	v_lshl_add_u64 v[230:231], v[36:37], 0, v[228:229]
	s_nop 0
	v_permlane16_swap_b32_e32 v224, v226
	v_permlane16_swap_b32_e32 v225, v227
	global_store_dwordx4 v[230:231], v[224:227], off
	s_nop 1
	v_pk_mul_f32 v[22:23], v[22:23], v[0:1] op_sel_hi:[1,0]
	s_waitcnt vmcnt(5)
	v_permlane16_swap_b32_e32 v232, v234
	v_permlane16_swap_b32_e32 v233, v235
	v_mov_b32_e32 v42, v232
	v_mov_b32_e32 v43, v233
	v_lshlrev_b32_e32 v26, 16, v42
	v_and_b32_e32 v27, 0xffff0000, v42
	v_pk_mul_f32 v[22:23], v[22:23], v[26:27]
	v_lshlrev_b32_e32 v26, 16, v43
	v_and_b32_e32 v27, 0xffff0000, v43
	v_pk_mul_f32 v[24:25], v[24:25], v[0:1] op_sel_hi:[1,0]
	v_cvt_pk_bf16_f32 v22, v22, v23
	v_pk_mul_f32 v[24:25], v[24:25], v[26:27]
	v_pk_mul_f32 v[18:19], v[18:19], v[0:1] op_sel_hi:[1,0]
	v_cvt_pk_bf16_f32 v23, v24, v25
	v_mov_b32_e32 v224, v22
	v_mov_b32_e32 v225, v23
	v_pk_mul_f32 v[20:21], v[20:21], v[0:1] op_sel_hi:[1,0]
	v_pk_mul_f32 v[14:15], v[14:15], v[0:1] op_sel_hi:[1,0]
	v_pk_mul_f32 v[16:17], v[16:17], v[0:1] op_sel_hi:[1,0]
	v_pk_mul_f32 v[10:11], v[10:11], v[0:1] op_sel_hi:[1,0]
	s_waitcnt vmcnt(5)
	v_mov_b32_e32 v40, v234
	v_mov_b32_e32 v41, v235
	v_lshlrev_b32_e32 v22, 16, v40
	v_and_b32_e32 v23, 0xffff0000, v40
	v_pk_mul_f32 v[18:19], v[18:19], v[22:23]
	v_lshlrev_b32_e32 v22, 16, v41
	v_and_b32_e32 v23, 0xffff0000, v41
	v_pk_mul_f32 v[20:21], v[20:21], v[22:23]
	v_cvt_pk_bf16_f32 v18, v18, v19
	v_cvt_pk_bf16_f32 v19, v20, v21
	v_mov_b32_e32 v226, v18
	v_mov_b32_e32 v227, v19
	v_lshl_add_u64 v[230:231], v[36:37], 0, v[228:229]
	s_nop 0
	v_permlane16_swap_b32_e32 v224, v226
	v_permlane16_swap_b32_e32 v225, v227
	global_store_dwordx4 v[230:231], v[224:227], off offset:64
	s_nop 1
	v_pk_mul_f32 v[12:13], v[12:13], v[0:1] op_sel_hi:[1,0]
	v_pk_mul_f32 v[6:7], v[6:7], v[0:1] op_sel_hi:[1,0]
	v_pk_mul_f32 v[8:9], v[8:9], v[0:1] op_sel_hi:[1,0]
	v_pk_mul_f32 v[2:3], v[2:3], v[0:1] op_sel_hi:[1,0]
	s_waitcnt vmcnt(4)
	v_permlane16_swap_b32_e32 v236, v238
	v_permlane16_swap_b32_e32 v237, v239
	v_mov_b32_e32 v44, v236
	v_mov_b32_e32 v45, v237
	v_lshlrev_b32_e32 v18, 16, v44
	v_and_b32_e32 v19, 0xffff0000, v44
	v_pk_mul_f32 v[14:15], v[14:15], v[18:19]
	v_lshlrev_b32_e32 v18, 16, v45
	v_and_b32_e32 v19, 0xffff0000, v45
	v_pk_mul_f32 v[16:17], v[16:17], v[18:19]
	v_cvt_pk_bf16_f32 v14, v14, v15
	v_cvt_pk_bf16_f32 v15, v16, v17
	v_mov_b32_e32 v224, v14
	v_mov_b32_e32 v225, v15
	v_pk_mul_f32 v[4:5], v[4:5], v[0:1] op_sel_hi:[1,0]
	s_mov_b64 s[0:1], 0
	s_waitcnt vmcnt(4)
	v_mov_b32_e32 v50, v238
	v_mov_b32_e32 v51, v239
	v_lshlrev_b32_e32 v14, 16, v50
	v_and_b32_e32 v15, 0xffff0000, v50
	v_pk_mul_f32 v[10:11], v[10:11], v[14:15]
	v_lshlrev_b32_e32 v14, 16, v51
	v_and_b32_e32 v15, 0xffff0000, v51
	v_pk_mul_f32 v[12:13], v[12:13], v[14:15]
	v_cvt_pk_bf16_f32 v10, v10, v11
	v_cvt_pk_bf16_f32 v11, v12, v13
	v_mov_b32_e32 v226, v10
	v_mov_b32_e32 v227, v11
	v_lshl_add_u64 v[230:231], v[36:37], 0, v[228:229]
	s_nop 0
	v_permlane16_swap_b32_e32 v224, v226
	v_permlane16_swap_b32_e32 v225, v227
	global_store_dwordx4 v[230:231], v[224:227], off offset:128
	s_nop 1
	s_waitcnt vmcnt(3)
	v_permlane16_swap_b32_e32 v240, v242
	v_permlane16_swap_b32_e32 v241, v243
	v_mov_b32_e32 v46, v240
	v_mov_b32_e32 v47, v241
	v_lshlrev_b32_e32 v10, 16, v46
	v_and_b32_e32 v11, 0xffff0000, v46
	v_pk_mul_f32 v[6:7], v[6:7], v[10:11]
	v_lshlrev_b32_e32 v10, 16, v47
	v_and_b32_e32 v11, 0xffff0000, v47
	v_pk_mul_f32 v[8:9], v[8:9], v[10:11]
	v_cvt_pk_bf16_f32 v6, v6, v7
	v_cvt_pk_bf16_f32 v7, v8, v9
	v_mov_b32_e32 v224, v6
	v_mov_b32_e32 v225, v7
	s_waitcnt vmcnt(3)
	v_mov_b32_e32 v34, v242
	v_mov_b32_e32 v35, v243
	v_lshlrev_b32_e32 v6, 16, v34
	v_and_b32_e32 v7, 0xffff0000, v34
	v_pk_mul_f32 v[2:3], v[2:3], v[6:7]
	v_lshlrev_b32_e32 v6, 16, v35
	v_and_b32_e32 v7, 0xffff0000, v35
	v_pk_mul_f32 v[4:5], v[4:5], v[6:7]
	v_cvt_pk_bf16_f32 v2, v2, v3
	v_cvt_pk_bf16_f32 v3, v4, v5
	v_mov_b32_e32 v226, v2
	v_mov_b32_e32 v227, v3
	v_lshl_add_u64 v[230:231], v[36:37], 0, v[228:229]
	s_nop 0
	v_permlane16_swap_b32_e32 v224, v226
	v_permlane16_swap_b32_e32 v225, v227
	global_store_dwordx4 v[230:231], v[224:227], off offset:192
	s_nop 1
